# gemm_in K loop: LDS-DMA addressed as scalar base + lane offset (4 SALU adds per step instead of 8 64-bit VALU adds)
# baseline (speedup 1.0000x reference)
; DI void gemm_dma(f32x4 (&acc)[4][4], const bf16_t* Ap, int lda, const bf16_t* Bp, int ldb, int K, char* lds) {
;   const int tid = tid_(), wave = __builtin_amdgcn_readfirstlane(tid >> 6), lane = tid & 63;
;   const int wm = wave >> 1, wn = wave & 1, l15 = lane & 15, quad = lane >> 4;
;   const int nk = K / 64;
;   const int lrow = lane >> 3, lpc = lane & 7;
;   const bf16_t* ga[4]; const bf16_t* gb[4];
; #pragma unroll
;   for (int i = 0; i < 4; ++i) {
;     const int row = (wave * 4 + i) * 8 + lrow; const int q = lpc ^ (row & 7);
;     ga[i] = Ap + (size_t)row * lda + q * 8; gb[i] = Bp + (size_t)row * ldb + q * 8;
;   }
;   auto issue = [&](int kt) {
;     char* sb = lds + (kt & 1) * 32768 + wave * 4096;
; #pragma unroll
;     for (int i = 0; i < 4; ++i) {
;       __builtin_amdgcn_global_load_lds((const unsigned*)(ga[i] + kt * 64), (LASP unsigned*)(sb + i * 1024), 16, 0, 0);
;       __builtin_amdgcn_global_load_lds((const unsigned*)(gb[i] + kt * 64), (LASP unsigned*)(sb + 16384 + i * 1024), 16, 0, 0);
;     }
;   };
;   const int sw = l15 & 7;
;   const unsigned lbase = (unsigned)(size_t)(LASP char*)lds;
;   const unsigned a0 = (unsigned)((wm * 64 + l15) * 128 + ((quad ^ sw) * 16)), a1 = (unsigned)((wm * 64 + l15) * 128 + (((4 + quad) ^ sw) * 16));
;   const unsigned b0 = 16384u + (unsigned)((wn * 64 + l15) * 128 + ((quad ^ sw) * 16)), b1 = 16384u + (unsigned)((wn * 64 + l15) * 128 + (((4 + quad) ^ sw) * 16));
;   asm volatile("s_waitcnt vmcnt(0)" ::: "memory");
;   __builtin_amdgcn_s_barrier();
; DI int xcd_tile(int r, int T) {
;   const int x = blockIdx.x & 7, j = blockIdx.x >> 3, nb = gridDim.x >> 3;
;   if (j >= nb) return -1;
;   const int start = (int)(((long)x * T) / 8), end = (int)(((long)(x + 1) * T) / 8);
;   const int g = start + r * nb + j;
;   return g < end ? g : -1;
; }
; DI void phase_gemm_in(const Params& p, int l, char* lds) {
;   const int tid = tid_(), wave = __builtin_amdgcn_readfirstlane(tid >> 6), lane = tid & 63;
;   const int wm = wave >> 1, wn = wave & 1, l15 = lane & 15, quad = lane >> 4;
;   const bf16_t* Wt = p.wt_in;
;   const int NTN = 49, NTM = 132;
;   for (int r = 0;; ++r) {
;     const int g = xcd_tile(r, NTN * NTM); if (g < 0) break;
;     int mt, nt; tile_decode(g, NTM, NTN, mt, nt);
;     f32x4 acc[4][4]; zero_acc(acc);
;     gemm_dma(acc, p.hn + (size_t)mt * 128 * DM, DM, Wt + (size_t)nt * 128 * DM, DM, DM, lds);
.LBB0_68:
	s_mul_hi_u32 s0, s20, 0x5397829d
	s_lshr_b32 s21, s0, 7
	s_lshl_b32 s0, s21, 3
	s_sub_i32 s1, 0x84, s0
	s_min_i32 s1, s1, 8
	s_abs_i32 s2, s1
	v_cvt_f32_u32_e32 v0, s2
	s_sub_i32 s24, 0, s2
	s_mul_i32 s3, s21, 0xfffffe78
	s_add_i32 s3, s3, s20
	v_rcp_iflag_f32_e32 v0, v0
	s_abs_i32 s22, s3
	s_xor_b32 s23, s3, s1
	s_ashr_i32 s23, s23, 31
	v_mul_f32_e32 v0, 0x4f7ffffe, v0
	v_cvt_u32_f32_e32 v0, v0
	v_readlane_b32 s68, v251, 49
	v_readlane_b32 s72, v251, 53
	v_mov_b32_e32 v26, v212
	v_readfirstlane_b32 s25, v0
	s_mul_i32 s24, s24, s25
	s_mul_hi_u32 s24, s25, s24
	s_add_i32 s25, s25, s24
	s_mul_hi_u32 s24, s22, s25
	s_mul_i32 s25, s24, s2
	s_sub_i32 s22, s22, s25
	s_add_i32 s26, s24, 1
	s_sub_i32 s25, s22, s2
	s_cmp_ge_u32 s22, s2
	s_cselect_b32 s24, s26, s24
	s_cselect_b32 s22, s25, s22
	s_add_i32 s25, s24, 1
	s_cmp_ge_u32 s22, s2
	s_cselect_b32 s2, s25, s24
	s_add_i32 s3, s3, s0
	s_xor_b32 s0, s2, s23
	s_sub_i32 s0, s0, s23
	s_mul_i32 s30, s0, s1
	s_sub_i32 s2, s3, s30
	s_ashr_i32 s3, s2, 31
	s_lshl_b64 s[22:23], s[2:3], 18
	s_add_u32 s24, s8, s22
	s_addc_u32 s25, s9, s23
	s_ashr_i32 s1, s0, 31
	s_lshl_b64 s[22:23], s[0:1], 18
	v_readlane_b32 s73, v251, 54
	s_add_u32 s26, s72, s22
	s_addc_u32 s27, s73, s23
	v_readfirstlane_b32 s1, v26
	s_ashr_i32 s3, s1, 6
	v_bfe_u32 v0, v26, 3, 3
	s_waitcnt lgkmcnt(0)
	v_lshl_or_b32 v2, s3, 5, v0
	v_bitop3_b32 v0, v0, v26, 7 bitop3:0x78
	v_bfe_u32 v27, v26, 4, 2
	v_and_b32_e32 v28, 7, v26
	v_lshlrev_b32_e32 v0, 4, v0
	v_ashrrev_i32_e32 v3, 31, v2
	v_and_b32_e32 v29, 15, v26
	v_lshl_add_u64 v[4:5], s[24:25], 0, v[0:1]
	v_lshlrev_b64 v[8:9], 11, v[2:3]
	v_or_b32_e32 v14, 8, v2
	s_lshr_b32 s24, s1, 1
	v_bitop3_b32 v26, v27, v26, 7 bitop3:0x78
	v_bitop3_b32 v27, v27, v28, 4 bitop3:0x36
	v_and_or_b32 v28, s1, 64, v29
	s_lshl_b32 s1, s3, 12
	v_lshl_add_u64 v[6:7], s[26:27], 0, v[0:1]
	v_lshl_add_u64 v[10:11], v[4:5], 0, v[8:9]
	v_ashrrev_i32_e32 v15, 31, v14
	s_waitcnt vmcnt(0)
	s_barrier
	s_add_i32 s3, s1, 0x4000
	s_mov_b32 m0, s1
	v_lshl_add_u64 v[12:13], v[6:7], 0, v[8:9]
	v_lshlrev_b64 v[14:15], 11, v[14:15]
	v_or_b32_e32 v20, 16, v2
	global_load_lds_dwordx4 v[10:11], off
	s_mov_b32 m0, s3
	v_lshl_add_u64 v[16:17], v[4:5], 0, v[14:15]
	v_ashrrev_i32_e32 v21, 31, v20
	global_load_lds_dwordx4 v[12:13], off
	s_or_b32 m0, s1, 0x400
	v_lshl_add_u64 v[18:19], v[6:7], 0, v[14:15]
	v_lshlrev_b64 v[20:21], 11, v[20:21]
	v_or_b32_e32 v2, 24, v2
	global_load_lds_dwordx4 v[16:17], off
	s_add_i32 m0, s1, 0x4400
	v_lshl_add_u64 v[22:23], v[4:5], 0, v[20:21]
	v_ashrrev_i32_e32 v3, 31, v2
	global_load_lds_dwordx4 v[18:19], off
	s_or_b32 m0, s1, 0x800
	v_lshl_add_u64 v[24:25], v[6:7], 0, v[20:21]
	v_lshlrev_b64 v[2:3], 11, v[2:3]
	global_load_lds_dwordx4 v[22:23], off
	s_add_i32 m0, s1, 0x4800
	v_lshl_add_u64 v[4:5], v[4:5], 0, v[2:3]
	global_load_lds_dwordx4 v[24:25], off
	s_or_b32 m0, s1, 0xc00
	v_lshl_add_u64 v[6:7], v[6:7], 0, v[2:3]
	global_load_lds_dwordx4 v[4:5], off
	s_add_i32 m0, s1, 0x4c00
	s_sub_i32 s3, s20, s30
	global_load_lds_dwordx4 v[6:7], off
	s_mulk_i32 s21, 0x180
	s_sub_i32 s20, s3, s21
	s_ashr_i32 s21, s20, 31
	s_and_b32 s24, s24, 0x1ffffc0
	s_lshl_b64 s[20:21], s[20:21], 18
	v_or_b32_e32 v30, s24, v29
	v_lshl_add_u64 v[4:5], s[20:21], 0, v[8:9]
	v_readlane_b32 s24, v254, 19
	v_or_b32_e32 v4, v4, v0
	v_readlane_b32 s25, v254, 20
	v_readlane_b32 s26, v254, 21
	v_readlane_b32 s27, v254, 22
	v_lshl_add_u64 v[66:67], s[24:25], 0, v[4:5]
	v_lshl_add_u64 v[4:5], s[22:23], 0, v[8:9]
	v_or_b32_e32 v4, v4, v0
	v_lshl_add_u64 v[68:69], s[26:27], 0, v[4:5]
	v_lshl_add_u64 v[4:5], s[20:21], 0, v[14:15]
	v_or_b32_e32 v4, v4, v0
	v_lshl_add_u64 v[74:75], s[24:25], 0, v[4:5]
	v_lshl_add_u64 v[4:5], s[22:23], 0, v[14:15]
	v_or_b32_e32 v4, v4, v0
	v_lshl_add_u64 v[76:77], s[26:27], 0, v[4:5]
	v_lshl_add_u64 v[4:5], s[20:21], 0, v[20:21]
	v_or_b32_e32 v4, v4, v0
	v_lshl_add_u64 v[78:79], s[24:25], 0, v[4:5]
	v_lshl_add_u64 v[4:5], s[22:23], 0, v[20:21]
	v_or_b32_e32 v4, v4, v0
	v_lshl_add_u64 v[80:81], s[26:27], 0, v[4:5]
	v_or_b32_e32 v222, v8, v0
	v_or_b32_e32 v223, v14, v0
	v_or_b32_e32 v224, v20, v0
	v_or_b32_e32 v225, v2, v0
	v_lshl_add_u64 v[4:5], s[20:21], 0, v[2:3]
	v_lshl_add_u64 v[2:3], s[22:23], 0, v[2:3]
	v_lshlrev_b32_e32 v30, 7, v30
	v_lshlrev_b32_e32 v26, 4, v26
	v_lshlrev_b32_e32 v27, 4, v27
	v_lshlrev_b32_e32 v28, 7, v28
	v_or_b32_e32 v4, v4, v0
	v_or_b32_e32 v2, v2, v0
	v_mov_b32_e32 v50, 0
	v_or_b32_e32 v86, v30, v26
	v_or_b32_e32 v87, v30, v27
	v_or3_b32 v89, v28, v26, s91
	v_or3_b32 v88, v28, v27, s91
	v_lshl_add_u64 v[82:83], s[24:25], 0, v[4:5]
	v_lshl_add_u64 v[84:85], s[26:27], 0, v[2:3]
	s_add_u32 s36, s24, s20
	s_addc_u32 s37, s25, s21
	s_add_u32 s38, s26, s22
	s_addc_u32 s39, s27, s23
	s_mov_b64 s[22:23], 0
	s_mov_b32 s3, 0
	v_mov_b32_e32 v51, v50
	v_mov_b32_e32 v52, v50
	v_mov_b32_e32 v53, v50
	v_mov_b32_e32 v2, v50
	v_mov_b32_e32 v3, v50
	v_mov_b32_e32 v4, v50
	v_mov_b32_e32 v5, v50
	v_mov_b32_e32 v6, v50
	v_mov_b32_e32 v7, v50
	v_mov_b32_e32 v8, v50
	v_mov_b32_e32 v9, v50
	v_mov_b32_e32 v10, v50
	v_mov_b32_e32 v11, v50
	v_mov_b32_e32 v12, v50
	v_mov_b32_e32 v13, v50
	v_mov_b32_e32 v14, v50
	v_mov_b32_e32 v15, v50
	v_mov_b32_e32 v16, v50
	v_mov_b32_e32 v17, v50
	v_mov_b32_e32 v18, v50
	v_mov_b32_e32 v19, v50
	v_mov_b32_e32 v20, v50
	v_mov_b32_e32 v21, v50
	v_mov_b32_e32 v22, v50
	v_mov_b32_e32 v23, v50
	v_mov_b32_e32 v24, v50
	v_mov_b32_e32 v25, v50
	v_mov_b32_e32 v26, v50
	v_mov_b32_e32 v27, v50
	v_mov_b32_e32 v28, v50
	v_mov_b32_e32 v29, v50
	v_mov_b32_e32 v30, v50
	v_mov_b32_e32 v31, v50
	v_mov_b32_e32 v32, v50
	v_mov_b32_e32 v33, v50
	v_mov_b32_e32 v34, v50
	v_mov_b32_e32 v35, v50
	v_mov_b32_e32 v36, v50
	v_mov_b32_e32 v37, v50
	v_mov_b32_e32 v38, v50
	v_mov_b32_e32 v39, v50
	v_mov_b32_e32 v40, v50
	v_mov_b32_e32 v41, v50
	v_mov_b32_e32 v42, v50
	v_mov_b32_e32 v43, v50
	v_mov_b32_e32 v44, v50
	v_mov_b32_e32 v45, v50
	v_mov_b32_e32 v46, v50
	v_mov_b32_e32 v47, v50
	v_mov_b32_e32 v48, v50
	v_mov_b32_e32 v49, v50
	v_mov_b32_e32 v54, v50
	v_mov_b32_e32 v55, v50
	v_mov_b32_e32 v56, v50
	v_mov_b32_e32 v57, v50
	v_mov_b32_e32 v58, v50
	v_mov_b32_e32 v59, v50
	v_mov_b32_e32 v60, v50
	v_mov_b32_e32 v61, v50
	v_mov_b32_e32 v62, v50
	v_mov_b32_e32 v63, v50
	v_mov_b32_e32 v64, v50
	v_mov_b32_e32 v65, v50
	v_readlane_b32 s69, v251, 50
	v_readlane_b32 s70, v251, 51
	v_readlane_b32 s71, v251, 52
	v_readlane_b32 s74, v251, 55
	v_readlane_b32 s75, v251, 56
	v_readlane_b32 s76, v251, 57
	v_readlane_b32 s77, v251, 58
	v_readlane_b32 s78, v251, 59
	v_readlane_b32 s79, v251, 60
	v_readlane_b32 s80, v251, 61
	v_readlane_b32 s81, v251, 62
	v_readlane_b32 s82, v251, 63
	v_readlane_b32 s83, v252, 0
; #define LASP __attribute__((address_space(3)))
; DI void gemm_dma(f32x4 (&acc)[4][4], const bf16_t* Ap, int lda, const bf16_t* Bp, int ldb, int K, char* lds) {
;     ...
;   auto issue = [&](int kt) {
;     char* sb = lds + (kt & 1) * 32768 + wave * 4096;
; #pragma unroll
;     for (int i = 0; i < 4; ++i) {
;       __builtin_amdgcn_global_load_lds((const unsigned*)(ga[i] + kt * 64), (LASP unsigned*)(sb + i * 1024), 16, 0, 0);
;       __builtin_amdgcn_global_load_lds((const unsigned*)(gb[i] + kt * 64), (LASP unsigned*)(sb + 16384 + i * 1024), 16, 0, 0);
;     }
;   };
;   const int sw = l15 & 7;
;   const unsigned lbase = (unsigned)(size_t)(LASP char*)lds;
;   const unsigned a0 = (unsigned)((wm * 64 + l15) * 128 + ((quad ^ sw) * 16)), a1 = (unsigned)((wm * 64 + l15) * 128 + (((4 + quad) ^ sw) * 16));
;   const unsigned b0 = 16384u + (unsigned)((wn * 64 + l15) * 128 + ((quad ^ sw) * 16)), b1 = 16384u + (unsigned)((wn * 64 + l15) * 128 + (((4 + quad) ^ sw) * 16));
;   asm volatile("s_waitcnt vmcnt(0)" ::: "memory");
;   __builtin_amdgcn_s_barrier();
;   asm volatile("" ::: "memory");
;   issue(0);
;   for (int kt = 0; kt < nk; ++kt) {
;     asm volatile("s_waitcnt vmcnt(0)" ::: "memory");
;     __builtin_amdgcn_s_barrier();
;     asm volatile("" ::: "memory");
;     if (kt + 1 < nk) issue(kt + 1);
;     const unsigned sa = lbase + (unsigned)((kt & 1) * 32768);
;     bf16x8 af[4], bfr[4], ag[4], bg[4];
;     asm volatile("ds_read_b128 %0, %8\n\tds_read_b128 %1, %8 offset:2048\n\tds_read_b128 %2, %8 offset:4096\n\tds_read_b128 %3, %8 offset:6144\n\t"
;                  "ds_read_b128 %4, %9\n\tds_read_b128 %5, %9 offset:2048\n\tds_read_b128 %6, %9 offset:4096\n\tds_read_b128 %7, %9 offset:6144"
;                  : "=&v"(af[0]), "=&v"(af[1]), "=&v"(af[2]), "=&v"(af[3]), "=&v"(bfr[0]), "=&v"(bfr[1]), "=&v"(bfr[2]), "=&v"(bfr[3])
;                  : "v"(sa + a0), "v"(sa + b0) : "memory");
;     asm volatile("ds_read_b128 %0, %16\n\tds_read_b128 %1, %16 offset:2048\n\tds_read_b128 %2, %16 offset:4096\n\tds_read_b128 %3, %16 offset:6144\n\t"
;                  "ds_read_b128 %4, %17\n\tds_read_b128 %5, %17 offset:2048\n\tds_read_b128 %6, %17 offset:4096\n\tds_read_b128 %7, %17 offset:6144\n\t"
;                  "s_waitcnt lgkmcnt(8)"
;                  : "=&v"(ag[0]), "=&v"(ag[1]), "=&v"(ag[2]), "=&v"(ag[3]), "=&v"(bg[0]), "=&v"(bg[1]), "=&v"(bg[2]), "=&v"(bg[3]),
.LBB0_69:
	s_add_i32 s20, s3, 0x8000
	s_and_b32 s3, s3, 0x8000
	s_and_b32 s21, s20, 0x8000
	v_add_u32_e32 v0, s3, v86
	v_or_b32_e32 v214, s3, v89
	v_add_u32_e32 v154, s3, v87
	v_add_u32_e32 v155, s3, v88
	s_add_i32 s3, s1, s21
	s_waitcnt vmcnt(0)
	s_barrier
	s_mov_b32 m0, s3
	s_nop 0
	global_load_lds_dwordx4 v222, s[36:37]
	s_add_i32 m0, s3, 0x4000
	s_nop 0
	global_load_lds_dwordx4 v222, s[38:39]
	s_add_i32 m0, s3, 0x400
	s_nop 0
	global_load_lds_dwordx4 v223, s[36:37]
	s_add_i32 m0, s3, 0x4400
	s_nop 0
	global_load_lds_dwordx4 v223, s[38:39]
	s_add_i32 m0, s3, 0x800
	s_nop 0
	global_load_lds_dwordx4 v224, s[36:37]
	s_add_i32 m0, s3, 0x4800
	s_nop 0
	global_load_lds_dwordx4 v224, s[38:39]
	s_add_i32 m0, s3, 0xc00
	s_nop 0
	global_load_lds_dwordx4 v225, s[36:37]
	s_add_i32 m0, s3, 0x4c00
	s_nop 0
	global_load_lds_dwordx4 v225, s[38:39]
	ds_read_b128 v[90:93], v0
	ds_read_b128 v[106:109], v214
	ds_read_b128 v[110:113], v214 offset:2048
	ds_read_b128 v[114:117], v214 offset:4096
	ds_read_b128 v[118:121], v214 offset:6144
	ds_read_b128 v[94:97], v0 offset:2048
	ds_read_b128 v[98:101], v0 offset:4096
	ds_read_b128 v[102:105], v0 offset:6144
	ds_read_b128 v[122:125], v154
	ds_read_b128 v[138:141], v155
	ds_read_b128 v[142:145], v155 offset:2048
	ds_read_b128 v[146:149], v155 offset:4096
	ds_read_b128 v[150:153], v155 offset:6144
	ds_read_b128 v[126:129], v154 offset:2048
	ds_read_b128 v[130:133], v154 offset:4096
	ds_read_b128 v[134:137], v154 offset:6144
	s_add_u32 s36, s36, 0x80
	s_addc_u32 s37, s37, 0
	s_add_u32 s38, s38, 0x80
	s_addc_u32 s39, s39, 0
	s_add_u32 s22, s22, 0x80
	s_cmpk_lg_i32 s22, 0x780
	s_waitcnt lgkmcnt(14)
	v_mfma_f32_16x16x32_bf16 v[62:65], v[106:109], v[90:93], v[62:65]
	s_waitcnt lgkmcnt(13)
	v_mfma_f32_16x16x32_bf16 v[58:61], v[110:113], v[90:93], v[58:61]
	s_waitcnt lgkmcnt(12)
	v_mfma_f32_16x16x32_bf16 v[54:57], v[114:117], v[90:93], v[54:57]
	s_waitcnt lgkmcnt(11)
	v_mfma_f32_16x16x32_bf16 v[46:49], v[118:121], v[90:93], v[46:49]
	s_waitcnt lgkmcnt(10)
	v_mfma_f32_16x16x32_bf16 v[42:45], v[106:109], v[94:97], v[42:45]
	v_mfma_f32_16x16x32_bf16 v[38:41], v[110:113], v[94:97], v[38:41]
	v_mfma_f32_16x16x32_bf16 v[34:37], v[114:117], v[94:97], v[34:37]
	v_mfma_f32_16x16x32_bf16 v[30:33], v[118:121], v[94:97], v[30:33]
	s_waitcnt lgkmcnt(9)
	v_mfma_f32_16x16x32_bf16 v[26:29], v[106:109], v[98:101], v[26:29]
	v_mfma_f32_16x16x32_bf16 v[22:25], v[110:113], v[98:101], v[22:25]
	v_mfma_f32_16x16x32_bf16 v[18:21], v[114:117], v[98:101], v[18:21]
	v_mfma_f32_16x16x32_bf16 v[14:17], v[118:121], v[98:101], v[14:17]
	s_waitcnt lgkmcnt(8)
	v_mfma_f32_16x16x32_bf16 v[10:13], v[106:109], v[102:105], v[10:13]
	v_mfma_f32_16x16x32_bf16 v[6:9], v[110:113], v[102:105], v[6:9]
	v_mfma_f32_16x16x32_bf16 v[2:5], v[114:117], v[102:105], v[2:5]
	v_mfma_f32_16x16x32_bf16 v[50:53], v[118:121], v[102:105], v[50:53]
	s_waitcnt lgkmcnt(6)
	v_mfma_f32_16x16x32_bf16 v[62:65], v[138:141], v[122:125], v[62:65]
	s_waitcnt lgkmcnt(5)
	v_mfma_f32_16x16x32_bf16 v[58:61], v[142:145], v[122:125], v[58:61]
	s_waitcnt lgkmcnt(4)
	v_mfma_f32_16x16x32_bf16 v[54:57], v[146:149], v[122:125], v[54:57]
	s_waitcnt lgkmcnt(3)
	v_mfma_f32_16x16x32_bf16 v[46:49], v[150:153], v[122:125], v[46:49]
	s_waitcnt lgkmcnt(2)
	v_mfma_f32_16x16x32_bf16 v[42:45], v[138:141], v[126:129], v[42:45]
	v_mfma_f32_16x16x32_bf16 v[38:41], v[142:145], v[126:129], v[38:41]
	v_mfma_f32_16x16x32_bf16 v[34:37], v[146:149], v[126:129], v[34:37]
	v_mfma_f32_16x16x32_bf16 v[30:33], v[150:153], v[126:129], v[30:33]
	s_waitcnt lgkmcnt(1)
	v_mfma_f32_16x16x32_bf16 v[26:29], v[138:141], v[130:133], v[26:29]
	v_mfma_f32_16x16x32_bf16 v[22:25], v[142:145], v[130:133], v[22:25]
	v_mfma_f32_16x16x32_bf16 v[18:21], v[146:149], v[130:133], v[18:21]
	v_mfma_f32_16x16x32_bf16 v[14:17], v[150:153], v[130:133], v[14:17]
	s_waitcnt lgkmcnt(0)
	v_mfma_f32_16x16x32_bf16 v[10:13], v[138:141], v[134:137], v[10:13]
	v_mfma_f32_16x16x32_bf16 v[6:9], v[142:145], v[134:137], v[6:9]
	v_mfma_f32_16x16x32_bf16 v[2:5], v[146:149], v[134:137], v[2:5]
	v_mfma_f32_16x16x32_bf16 v[50:53], v[150:153], v[134:137], v[50:53]
	s_mov_b32 s3, s20
	s_cbranch_scc1 .LBB0_69
; DI void gemm_dma(f32x4 (&acc)[4][4], const bf16_t* Ap, int lda, const bf16_t* Bp, int ldb, int K, char* lds) {
;     ...
;   for (int kt = 0; kt < nk; ++kt) {
;     asm volatile("s_waitcnt vmcnt(0)" ::: "memory");
;     __builtin_amdgcn_s_barrier();
;     asm volatile("" ::: "memory");
;     if (kt + 1 < nk) issue(kt + 1);
;     const unsigned sa = lbase + (unsigned)((kt & 1) * 32768);
;     bf16x8 af[4], bfr[4], ag[4], bg[4];
;     asm volatile("ds_read_b128 %0, %8\n\tds_read_b128 %1, %8 offset:2048\n\tds_read_b128 %2, %8 offset:4096\n\tds_read_b128 %3, %8 offset:6144\n\t"
;                  "ds_read_b128 %4, %9\n\tds_read_b128 %5, %9 offset:2048\n\tds_read_b128 %6, %9 offset:4096\n\tds_read_b128 %7, %9 offset:6144"
;                  : "=&v"(af[0]), "=&v"(af[1]), "=&v"(af[2]), "=&v"(af[3]), "=&v"(bfr[0]), "=&v"(bfr[1]), "=&v"(bfr[2]), "=&v"(bfr[3])
;                  : "v"(sa + a0), "v"(sa + b0) : "memory");
;     asm volatile("ds_read_b128 %0, %16\n\tds_read_b128 %1, %16 offset:2048\n\tds_read_b128 %2, %16 offset:4096\n\tds_read_b128 %3, %16 offset:6144\n\t"
;                  "ds_read_b128 %4, %17\n\tds_read_b128 %5, %17 offset:2048\n\tds_read_b128 %6, %17 offset:4096\n\tds_read_b128 %7, %17 offset:6144\n\t"
;                  "s_waitcnt lgkmcnt(8)"
;                  : "=&v"(ag[0]), "=&v"(ag[1]), "=&v"(ag[2]), "=&v"(ag[3]), "=&v"(bg[0]), "=&v"(bg[1]), "=&v"(bg[2]), "=&v"(bg[3]),
;                    "+v"(af[0]), "+v"(af[1]), "+v"(af[2]), "+v"(af[3]), "+v"(bfr[0]), "+v"(bfr[1]), "+v"(bfr[2]), "+v"(bfr[3])
;                  : "v"(sa + a1), "v"(sa + b1) : "memory");
; #pragma unroll
;     for (int mi = 0; mi < 4; ++mi)
; #pragma unroll
;       for (int ni = 0; ni < 4; ++ni) acc[mi][ni] = __builtin_amdgcn_mfma_f32_16x16x32_bf16(bfr[ni], af[mi], acc[mi][ni], 0, 0, 0);
;     asm volatile("s_waitcnt lgkmcnt(0)" : "+v"(ag[0]), "+v"(ag[1]), "+v"(ag[2]), "+v"(ag[3]), "+v"(bg[0]), "+v"(bg[1]), "+v"(bg[2]), "+v"(bg[3]) :: "memory");
; #pragma unroll
;     for (int mi = 0; mi < 4; ++mi)
; #pragma unroll
;       for (int ni = 0; ni < 4; ++ni) acc[mi][ni] = __builtin_amdgcn_mfma_f32_16x16x32_bf16(bg[ni], ag[mi], acc[mi][ni], 0, 0, 0);
;   }
;   asm volatile("" ::: "memory");
;   __builtin_amdgcn_s_barrier();
;   asm volatile("" ::: "memory");
	s_waitcnt vmcnt(0)
	s_barrier
	v_add_u32_e32 v0, 0x8000, v86
	v_or_b32_e32 v86, 0x8000, v89
	ds_read_b128 v[66:69], v0
	ds_read_b128 v[74:77], v0 offset:2048
	ds_read_b128 v[78:81], v0 offset:4096
	ds_read_b128 v[82:85], v0 offset:6144
	ds_read_b128 v[90:93], v86
	ds_read_b128 v[94:97], v86 offset:2048
	ds_read_b128 v[98:101], v86 offset:4096
	ds_read_b128 v[102:105], v86 offset:6144
	v_add_u32_e32 v0, 0x8000, v87
	v_add_u32_e32 v134, 0x8000, v88
	ds_read_b128 v[86:89], v0
	ds_read_b128 v[106:109], v0 offset:2048
	ds_read_b128 v[110:113], v0 offset:4096
	ds_read_b128 v[114:117], v0 offset:6144
	ds_read_b128 v[118:121], v134
	ds_read_b128 v[122:125], v134 offset:2048
	ds_read_b128 v[126:129], v134 offset:4096
	ds_read_b128 v[130:133], v134 offset:6144
	s_waitcnt lgkmcnt(8)
	s_lshl_b32 s46, s2, 7
	v_mfma_f32_16x16x32_bf16 v[62:65], v[90:93], v[66:69], v[62:65]
	s_waitcnt lgkmcnt(0)
	v_readlane_b32 s20, v254, 52
	v_readlane_b32 s21, v254, 53
	v_mfma_f32_16x16x32_bf16 v[46:49], v[102:105], v[66:69], v[46:49]
	s_barrier
	v_mfma_f32_16x16x32_bf16 v[42:45], v[90:93], v[74:77], v[42:45]
	v_readlane_b32 s22, v254, 54
	v_readlane_b32 s23, v254, 55
	v_readlane_b32 s24, v254, 56
	v_mfma_f32_16x16x32_bf16 v[38:41], v[94:97], v[74:77], v[38:41]
	v_readlane_b32 s25, v254, 57
	v_readlane_b32 s26, v254, 58
	v_readlane_b32 s27, v254, 59
	v_mfma_f32_16x16x32_bf16 v[34:37], v[98:101], v[74:77], v[34:37]
	s_cmp_gt_i32 s0, 12
	s_mov_b64 s[2:3], 0
	s_cselect_b64 s[30:31], -1, 0
	v_mfma_f32_16x16x32_bf16 v[30:33], v[102:105], v[74:77], v[30:33]
	s_cmp_lt_i32 s0, 13
	s_mov_b64 s[26:27], 0
	s_mov_b64 s[24:25], 0
	v_mfma_f32_16x16x32_bf16 v[26:29], v[90:93], v[78:81], v[26:29]
	s_mov_b64 s[22:23], 0
	v_mfma_f32_16x16x32_bf16 v[18:21], v[98:101], v[78:81], v[18:21]
	v_mfma_f32_16x16x32_bf16 v[14:17], v[102:105], v[78:81], v[14:17]
	v_mfma_f32_16x16x32_bf16 v[134:137], v[98:101], v[66:69], v[54:57]
	v_mfma_f32_16x16x32_bf16 v[54:57], v[118:121], v[86:89], v[62:65]
	v_mfma_f32_16x16x32_bf16 v[62:65], v[130:133], v[86:89], v[46:49]
	v_mfma_f32_16x16x32_bf16 v[46:49], v[118:121], v[106:109], v[42:45]
	v_mfma_f32_16x16x32_bf16 v[42:45], v[122:125], v[106:109], v[38:41]
	v_mfma_f32_16x16x32_bf16 v[38:41], v[126:129], v[106:109], v[34:37]
	v_mfma_f32_16x16x32_bf16 v[34:37], v[130:133], v[106:109], v[30:33]
	v_mfma_f32_16x16x32_bf16 v[30:33], v[118:121], v[110:113], v[26:29]
	v_mfma_f32_16x16x32_bf16 v[26:29], v[126:129], v[110:113], v[18:21]
	v_mfma_f32_16x16x32_bf16 v[18:21], v[130:133], v[110:113], v[14:17]
	s_nop 2
	v_add_u32_e32 v14, s46, v71
	v_ashrrev_i32_e32 v15, 31, v14
	v_lshl_add_u64 v[74:75], v[14:15], 2, s[20:21]
	v_mfma_f32_16x16x32_bf16 v[58:61], v[94:97], v[66:69], v[58:61]
	v_mfma_f32_16x16x32_bf16 v[66:69], v[102:105], v[82:85], v[50:53]
	global_load_dword v0, v[74:75], off
	global_load_dword v105, v[74:75], off offset:64
	global_load_dword v104, v[74:75], off offset:128
	global_load_dword v102, v[74:75], off offset:192
	v_mfma_f32_16x16x32_bf16 v[22:25], v[94:97], v[78:81], v[22:25]
	v_mfma_f32_16x16x32_bf16 v[10:13], v[90:93], v[82:85], v[10:13]
	v_mfma_f32_16x16x32_bf16 v[6:9], v[94:97], v[82:85], v[6:9]
	v_mfma_f32_16x16x32_bf16 v[2:5], v[98:101], v[82:85], v[2:5]
	v_mfma_f32_16x16x32_bf16 v[50:53], v[122:125], v[86:89], v[58:61]
	v_mfma_f32_16x16x32_bf16 v[58:61], v[126:129], v[86:89], v[134:137]
	v_mfma_f32_16x16x32_bf16 v[22:25], v[122:125], v[110:113], v[22:25]
	v_mfma_f32_16x16x32_bf16 v[14:17], v[118:121], v[114:117], v[10:13]
	v_mfma_f32_16x16x32_bf16 v[10:13], v[122:125], v[114:117], v[6:9]
	v_mfma_f32_16x16x32_bf16 v[6:9], v[126:129], v[114:117], v[2:5]
	v_mfma_f32_16x16x32_bf16 v[2:5], v[130:133], v[114:117], v[66:69]
	s_cbranch_scc1 .LBB0_77
	s_cmp_lt_u32 s0, 17
	s_cbranch_scc1 .LBB0_75
	s_cmp_lt_u32 s0, 21
	s_cbranch_scc1 .LBB0_76
	s_mov_b64 s[22:23], -1
	s_cmp_lt_u32 s0, 25
	s_cbranch_scc1 .LBB0_77
	s_sub_i32 s1, s0, 29
	s_cmp_lt_u32 s1, 4
	s_cselect_b64 s[2:3], -1, 0
	s_cmp_gt_u32 s0, 32
	s_mov_b64 s[22:23], 0
	s_cselect_b64 s[26:27], -1, 0
	s_branch .LBB0_77
